# w_o GEMM sample rows split K 8 ways (was 4); LN1 sums 8 slabs with the slab-heavy rows given to waves that have one row fewer
# speedup vs baseline: 1.0065x; 1.0018x over previous
.LBB0_1409:
	s_cmp_lt_i32 s56, 7
	s_cselect_b64 s[4:5], -1, 0
	s_and_b64 s[6:7], s[4:5], s[0:1]
	s_andn2_b64 vcc, exec, s[6:7]
	s_cbranch_vccnz .LBB0_1515
	s_cmpk_gt_i32 s2, 0xff
	v_readfirstlane_b32 s14, v166
	s_cbranch_scc0 .LBB0_1413
	s_and_b32 s0, s2, 0x7fffffc0
	s_mov_b64 s[8:9], 0
	s_cmpk_lg_i32 s0, 0x100
	s_mov_b64 s[4:5], 0
	s_cbranch_scc1 .LBB0_1414
	s_lshl_b32 s1, s2, 5
	s_and_b32 s0, s2, 7
	s_and_b32 s34, s1, 0x700
	s_mov_b32 s61, 1
	s_mov_b32 s62, 4
	s_mov_b32 s30, 32
	s_mov_b64 s[4:5], -1
	s_branch .LBB0_1414

.LBB0_1426:
	s_add_i32 s58, s58, 1
	s_mul_i32 s1, s58, s51
	s_mul_hi_u32 s4, s58, s33
	s_add_i32 s1, s4, s1
	s_mul_i32 s4, s58, s33
	s_add_u32 s4, s4, s2
	s_addc_u32 s5, s1, s52
	v_cmp_gt_i64_e32 vcc, s[4:5], v[154:155]
	s_mov_b64 s[28:29], -1
	s_cbranch_vccz .LBB0_1429
	s_add_i32 s1, s4, 0xffffff00
	s_mov_b64 s[28:29], 0
	s_cmp_gt_i32 s1, 63
	s_mov_b64 s[26:27], 0
	s_cbranch_scc1 .LBB0_1429
	s_ashr_i32 s5, s1, 31
	s_lshr_b32 s5, s5, 29
	s_add_i32 s5, s1, s5
	s_and_b32 s20, s5, -8
	s_sub_i32 s22, s1, s20
	s_lshl_b32 s1, s5, 5
	s_and_b32 s20, s1, 0xffffff00
	s_mov_b32 s60, 1
	s_mov_b32 s59, 4
	s_mov_b32 s24, 32
	s_mov_b64 s[26:27], -1

.LBB0_1443:
	s_cmp_eq_u32 s61, 0
	s_cbranch_scc1 .LBB0_1494
	s_ashr_i32 s1, s34, 31
	s_lshr_b32 s1, s1, 24
	s_add_i32 s1, s34, s1
	s_ashr_i32 s34, s1, 8
	s_ashr_i32 s35, s34, 31
	s_lshl_b64 s[34:35], s[34:35], 20
	v_lshl_add_u64 v[128:129], v[148:149], 0, s[34:35]
	s_lshl_b32 s34, s0, 8
	s_ashr_i32 s35, s34, 31
	v_lshl_add_u64 v[128:129], s[34:35], 2, v[128:129]
	v_lshl_add_u64 v[128:129], v[128:129], 0, s[8:9]
	v_lshl_add_u64 v[128:129], v[128:129], 0, v[144:145]
	v_add_co_u32_e32 v130, vcc, s55, v128
	global_store_dwordx4 v[128:129], v[124:127], off
	global_store_dwordx4 v[128:129], v[120:123], off offset:16
	global_store_dwordx4 v[128:129], v[116:119], off offset:512
	global_store_dwordx4 v[128:129], v[112:115], off offset:528
	v_addc_co_u32_e32 v131, vcc, 0, v129, vcc
	global_store_dwordx4 v[130:131], v[108:111], off
	global_store_dwordx4 v[130:131], v[104:107], off offset:16
	global_store_dwordx4 v[130:131], v[100:103], off offset:512
	global_store_dwordx4 v[130:131], v[96:99], off offset:528
	v_add_co_u32_e32 v130, vcc, 0x40000, v128
	s_nop 1
	v_addc_co_u32_e32 v131, vcc, 0, v129, vcc
	v_add_co_u32_e32 v128, vcc, 0x60000, v128
	global_store_dwordx4 v[130:131], v[92:95], off
	global_store_dwordx4 v[130:131], v[88:91], off offset:16
	global_store_dwordx4 v[130:131], v[84:87], off offset:512
	global_store_dwordx4 v[130:131], v[80:83], off offset:528
	v_addc_co_u32_e32 v129, vcc, 0, v129, vcc
	global_store_dwordx4 v[128:129], v[76:79], off
	global_store_dwordx4 v[128:129], v[72:75], off offset:16
	global_store_dwordx4 v[128:129], v[68:71], off offset:512
	global_store_dwordx4 v[128:129], v[64:67], off offset:528
	s_cbranch_execnz .LBB0_1495

.LBB0_1573:
	v_add_u32_e32 v1, 0xffffff80, v33
	v_cmp_gt_i32_e32 vcc, s26, v33
	v_add_u32_e32 v0, 0x1f80, v33
	s_nop 0
	v_cndmask_b32_e32 v1, v33, v1, vcc
	v_cmp_gt_u32_e32 vcc, s19, v1
	s_nop 1
	v_cndmask_b32_e32 v96, v1, v0, vcc
	v_cmp_gt_i32_e32 vcc, s19, v33
	s_nop 1
	v_cndmask_b32_e32 v96, v96, v33, vcc
	v_cmp_gt_i32_e32 vcc, s26, v96
	s_and_saveexec_b64 s[6:7], vcc
	s_xor_b64 s[6:7], exec, s[6:7]
	s_cbranch_execz .LBB0_1595
	v_cmp_lt_i32_e32 vcc, s27, v96
	v_lshlrev_b32_e32 v94, 4, v32
	v_lshlrev_b32_e32 v92, 4, v36
	v_lshlrev_b32_e32 v90, 4, v38
	v_lshlrev_b32_e32 v88, 4, v40
	v_lshlrev_b32_e32 v86, 4, v42
	s_and_saveexec_b64 s[24:25], vcc
	s_xor_b64 s[24:25], exec, s[24:25]
	s_cbranch_execz .LBB0_1576
	v_add_u32_e32 v0, 0xffffe000, v96
	v_mov_b32_e32 v1, v35
	v_readlane_b32 s36, v239, 17
	v_lshlrev_b64 v[98:99], 13, v[0:1]
	v_readlane_b32 s38, v239, 19
	v_readlane_b32 s39, v239, 20
	v_mov_b32_e32 v95, v35
	v_mov_b32_e32 v93, v35
	v_lshl_add_u64 v[24:25], s[38:39], 0, v[98:99]
	v_mov_b32_e32 v91, v35
	v_mov_b32_e32 v89, v35
	v_mov_b32_e32 v87, v35
	v_lshl_add_u64 v[196:197], s[14:15], 0, v[98:99]
	v_lshl_add_u64 v[0:1], v[24:25], 0, v[94:95]
	v_lshl_add_u64 v[16:17], v[24:25], 0, v[92:93]
	v_lshl_add_u64 v[20:21], v[24:25], 0, v[90:91]
	v_lshl_add_u64 v[26:27], v[24:25], 0, v[88:89]
	v_lshl_add_u64 v[28:29], v[24:25], 0, v[86:87]
	v_lshl_add_u64 v[110:111], v[196:197], 0, v[94:95]
	v_lshl_add_u64 v[114:115], v[196:197], 0, v[92:93]
	v_lshl_add_u64 v[118:119], v[196:197], 0, v[90:91]
	v_lshl_add_u64 v[154:155], v[196:197], 0, s[12:13]
	v_mov_b32_e32 v67, v35
	v_mov_b32_e32 v69, v35
	v_mov_b32_e32 v71, v35
	global_load_dwordx4 v[12:15], v[0:1], off
	global_load_dwordx4 v[8:11], v[0:1], off offset:1024
	global_load_dwordx4 v[4:7], v[0:1], off offset:2048
	s_nop 0
	global_load_dwordx4 v[0:3], v[0:1], off offset:3072
	s_nop 0
	global_load_dwordx4 v[16:19], v[16:17], off
	s_nop 0
	global_load_dwordx4 v[20:23], v[20:21], off
	s_nop 0
	global_load_dwordx4 v[24:27], v[26:27], off
	s_nop 0
	global_load_dwordx4 v[28:31], v[28:29], off
	s_nop 0
	global_load_dwordx4 v[98:101], v[110:111], off
	global_load_dwordx4 v[102:105], v[110:111], off offset:1024
	global_load_dwordx4 v[106:109], v[110:111], off offset:2048
	s_nop 0
	global_load_dwordx4 v[110:113], v[110:111], off offset:3072
	s_nop 0
	global_load_dwordx4 v[114:117], v[114:115], off
	s_nop 0
	global_load_dwordx4 v[118:121], v[118:119], off
	v_lshl_add_u64 v[122:123], v[196:197], 0, v[88:89]
	v_lshl_add_u64 v[126:127], v[196:197], 0, v[86:87]
	v_lshl_add_u64 v[130:131], v[154:155], 0, v[94:95]
	v_lshl_add_u64 v[134:135], v[154:155], 0, v[66:67]
	v_lshl_add_u64 v[138:139], v[154:155], 0, v[68:69]
	v_lshl_add_u64 v[142:143], v[154:155], 0, v[70:71]
	v_lshl_add_u64 v[146:147], v[154:155], 0, v[92:93]
	v_lshl_add_u64 v[150:151], v[154:155], 0, v[90:91]
	v_lshl_add_u64 v[188:189], v[196:197], 0, s[20:21]
	global_load_dwordx4 v[122:125], v[122:123], off
	s_nop 0
	global_load_dwordx4 v[126:129], v[126:127], off
	s_nop 0
	global_load_dwordx4 v[130:133], v[130:131], off
	s_nop 0
	global_load_dwordx4 v[134:137], v[134:135], off
	s_nop 0
	global_load_dwordx4 v[138:141], v[138:139], off
	s_nop 0
	global_load_dwordx4 v[142:145], v[142:143], off
	s_nop 0
	global_load_dwordx4 v[146:149], v[146:147], off
	s_nop 0
	global_load_dwordx4 v[150:153], v[150:151], off
	v_lshl_add_u64 v[156:157], v[154:155], 0, v[88:89]
	v_lshl_add_u64 v[158:159], v[154:155], 0, v[86:87]
	v_lshl_add_u64 v[162:163], v[188:189], 0, v[94:95]
	v_lshl_add_u64 v[168:169], v[188:189], 0, v[66:67]
	v_lshl_add_u64 v[172:173], v[188:189], 0, v[68:69]
	v_lshl_add_u64 v[176:177], v[188:189], 0, v[70:71]
	v_lshl_add_u64 v[180:181], v[188:189], 0, v[92:93]
	v_lshl_add_u64 v[184:185], v[188:189], 0, v[90:91]
	v_lshl_add_u64 v[224:225], v[196:197], 0, s[22:23]
	global_load_dwordx4 v[154:157], v[156:157], off
	s_nop 0
	global_load_dwordx4 v[158:161], v[158:159], off
	s_nop 0
	global_load_dwordx4 v[162:165], v[162:163], off
	s_nop 0
	global_load_dwordx4 v[168:171], v[168:169], off
	s_nop 0
	global_load_dwordx4 v[172:175], v[172:173], off
	s_nop 0
	global_load_dwordx4 v[176:179], v[176:177], off
	s_nop 0
	global_load_dwordx4 v[180:183], v[180:181], off
	s_nop 0
	global_load_dwordx4 v[184:187], v[184:185], off
	v_lshl_add_u64 v[190:191], v[188:189], 0, v[88:89]
	v_lshl_add_u64 v[192:193], v[188:189], 0, v[86:87]
	v_lshl_add_u64 v[196:197], v[224:225], 0, v[94:95]
	v_lshl_add_u64 v[200:201], v[224:225], 0, v[66:67]
	v_lshl_add_u64 v[204:205], v[224:225], 0, v[68:69]
	v_lshl_add_u64 v[212:213], v[224:225], 0, v[92:93]
	v_lshl_add_u64 v[216:217], v[224:225], 0, v[90:91]
	global_load_dwordx4 v[188:191], v[190:191], off
	s_nop 0
	global_load_dwordx4 v[192:195], v[192:193], off
	v_lshl_add_u64 v[208:209], v[224:225], 0, v[70:71]
	global_load_dwordx4 v[196:199], v[196:197], off
	v_lshl_add_u64 v[220:221], v[224:225], 0, v[88:89]
	global_load_dwordx4 v[200:203], v[200:201], off
	v_lshl_add_u64 v[224:225], v[224:225], 0, v[86:87]
	global_load_dwordx4 v[204:207], v[204:205], off
	v_readlane_b32 s37, v239, 18
	global_load_dwordx4 v[212:215], v[212:213], off
	v_readlane_b32 s40, v239, 21
	global_load_dwordx4 v[216:219], v[216:217], off
	v_readlane_b32 s41, v239, 22
	global_load_dwordx4 v[208:211], v[208:209], off
	v_readlane_b32 s42, v239, 23
	global_load_dwordx4 v[220:223], v[220:221], off
	v_readlane_b32 s43, v239, 24
	global_load_dwordx4 v[224:227], v[224:225], off
	v_readlane_b32 s44, v239, 25
	v_readlane_b32 s45, v239, 26
	v_readlane_b32 s46, v239, 27
	v_readlane_b32 s47, v239, 28
	v_readlane_b32 s48, v239, 29
	v_readlane_b32 s49, v239, 30
	v_readlane_b32 s50, v239, 31
	v_readlane_b32 s51, v239, 32
	s_waitcnt vmcnt(31)
	v_pk_fma_f32 v[14:15], v[14:15], s[18:19], v[100:101] op_sel_hi:[1,0,1]
	v_pk_fma_f32 v[12:13], v[12:13], s[18:19], v[98:99] op_sel_hi:[1,0,1]
	s_waitcnt vmcnt(30)
	v_pk_fma_f32 v[10:11], v[10:11], s[18:19], v[104:105] op_sel_hi:[1,0,1]
	v_pk_fma_f32 v[8:9], v[8:9], s[18:19], v[102:103] op_sel_hi:[1,0,1]
	s_waitcnt vmcnt(29)
	v_pk_fma_f32 v[6:7], v[6:7], s[18:19], v[108:109] op_sel_hi:[1,0,1]
	v_pk_fma_f32 v[4:5], v[4:5], s[18:19], v[106:107] op_sel_hi:[1,0,1]
	s_waitcnt vmcnt(27)
	v_pk_fma_f32 v[18:19], v[18:19], s[18:19], v[116:117] op_sel_hi:[1,0,1]
	v_pk_fma_f32 v[16:17], v[16:17], s[18:19], v[114:115] op_sel_hi:[1,0,1]
	s_waitcnt vmcnt(26)
	v_pk_fma_f32 v[22:23], v[22:23], s[18:19], v[120:121] op_sel_hi:[1,0,1]
	v_pk_fma_f32 v[20:21], v[20:21], s[18:19], v[118:119] op_sel_hi:[1,0,1]
	v_pk_fma_f32 v[2:3], v[2:3], s[18:19], v[112:113] op_sel_hi:[1,0,1]
	v_pk_fma_f32 v[0:1], v[0:1], s[18:19], v[110:111] op_sel_hi:[1,0,1]
	s_waitcnt vmcnt(25)
	v_pk_fma_f32 v[26:27], v[26:27], s[18:19], v[124:125] op_sel_hi:[1,0,1]
	v_pk_fma_f32 v[24:25], v[24:25], s[18:19], v[122:123] op_sel_hi:[1,0,1]
	s_waitcnt vmcnt(24)
	v_pk_fma_f32 v[30:31], v[30:31], s[18:19], v[128:129] op_sel_hi:[1,0,1]
	v_pk_fma_f32 v[28:29], v[28:29], s[18:19], v[126:127] op_sel_hi:[1,0,1]
	s_waitcnt vmcnt(23)
	v_pk_add_f32 v[14:15], v[14:15], v[132:133]
	v_pk_add_f32 v[12:13], v[12:13], v[130:131]
	s_waitcnt vmcnt(22)
	v_pk_add_f32 v[10:11], v[10:11], v[136:137]
	v_pk_add_f32 v[8:9], v[8:9], v[134:135]
	s_waitcnt vmcnt(21)
	v_pk_add_f32 v[6:7], v[6:7], v[140:141]
	v_pk_add_f32 v[4:5], v[4:5], v[138:139]
	s_waitcnt vmcnt(19)
	v_pk_add_f32 v[18:19], v[18:19], v[148:149]
	v_pk_add_f32 v[16:17], v[16:17], v[146:147]
	s_waitcnt vmcnt(18)
	v_pk_add_f32 v[22:23], v[22:23], v[152:153]
	v_pk_add_f32 v[20:21], v[20:21], v[150:151]
	v_pk_add_f32 v[2:3], v[2:3], v[144:145]
	v_pk_add_f32 v[0:1], v[0:1], v[142:143]
	s_waitcnt vmcnt(17)
	v_pk_add_f32 v[26:27], v[26:27], v[156:157]
	v_pk_add_f32 v[24:25], v[24:25], v[154:155]
	s_waitcnt vmcnt(16)
	v_pk_add_f32 v[30:31], v[30:31], v[160:161]
	v_pk_add_f32 v[28:29], v[28:29], v[158:159]
	s_waitcnt vmcnt(15)
	v_pk_add_f32 v[14:15], v[14:15], v[164:165]
	v_pk_add_f32 v[12:13], v[12:13], v[162:163]
	s_waitcnt vmcnt(14)
	v_pk_add_f32 v[10:11], v[10:11], v[170:171]
	v_pk_add_f32 v[8:9], v[8:9], v[168:169]
	s_waitcnt vmcnt(13)
	v_pk_add_f32 v[6:7], v[6:7], v[174:175]
	v_pk_add_f32 v[4:5], v[4:5], v[172:173]
	s_waitcnt vmcnt(11)
	v_pk_add_f32 v[98:99], v[18:19], v[182:183]
	v_pk_add_f32 v[100:101], v[16:17], v[180:181]
	s_waitcnt vmcnt(10)
	v_pk_add_f32 v[22:23], v[22:23], v[186:187]
	v_pk_add_f32 v[102:103], v[20:21], v[184:185]
	v_pk_add_f32 v[2:3], v[2:3], v[178:179]
	v_pk_add_f32 v[0:1], v[0:1], v[176:177]
	s_waitcnt vmcnt(9)
	v_pk_add_f32 v[26:27], v[26:27], v[190:191]
	v_pk_add_f32 v[24:25], v[24:25], v[188:189]
	s_waitcnt vmcnt(8)
	v_pk_add_f32 v[30:31], v[30:31], v[194:195]
	v_pk_add_f32 v[28:29], v[28:29], v[192:193]
	s_waitcnt vmcnt(7)
	v_pk_add_f32 v[112:113], v[14:15], v[198:199]
	v_pk_add_f32 v[114:115], v[12:13], v[196:197]
	s_waitcnt vmcnt(6)
	v_pk_add_f32 v[106:107], v[10:11], v[202:203]
	v_pk_add_f32 v[108:109], v[8:9], v[200:201]
	s_waitcnt vmcnt(5)
	v_pk_add_f32 v[20:21], v[6:7], v[206:207]
	v_pk_add_f32 v[10:11], v[4:5], v[204:205]
	s_waitcnt vmcnt(4)
	v_pk_add_f32 v[14:15], v[98:99], v[214:215]
	v_pk_add_f32 v[12:13], v[100:101], v[212:213]
	s_waitcnt vmcnt(3)
	v_pk_add_f32 v[8:9], v[22:23], v[218:219]
	v_pk_add_f32 v[22:23], v[102:103], v[216:217]
	s_waitcnt vmcnt(2)
	v_pk_add_f32 v[18:19], v[2:3], v[210:211]
	v_pk_add_f32 v[16:17], v[0:1], v[208:209]
	s_waitcnt vmcnt(1)
	v_pk_add_f32 v[6:7], v[26:27], v[222:223]
	v_pk_add_f32 v[4:5], v[24:25], v[220:221]
	s_waitcnt vmcnt(0)
	v_pk_add_f32 v[2:3], v[30:31], v[226:227]
	v_pk_add_f32 v[0:1], v[28:29], v[224:225]
	v_add_u32_e32 v196, 0xffffe000, v96
	v_mov_b32_e32 v197, 0
	v_lshlrev_b64 v[196:197], 13, v[196:197]
	v_lshl_add_u64 v[196:197], s[14:15], 0, v[196:197]
	v_lshl_add_u64 v[196:197], v[196:197], 0, v[94:95]
	s_mov_b32 vcc_lo, 0x400000
	s_mov_b32 vcc_hi, 0
	v_lshl_add_u64 v[198:199], v[196:197], 0, vcc
	s_mov_b32 vcc_lo, 0x401000
	v_lshl_add_u64 v[200:201], v[196:197], 0, vcc
	global_load_dwordx4 v[128:131], v[198:199], off
	global_load_dwordx4 v[132:135], v[198:199], off offset:1024
	global_load_dwordx4 v[136:139], v[198:199], off offset:2048
	global_load_dwordx4 v[140:143], v[198:199], off offset:3072
	global_load_dwordx4 v[144:147], v[200:201], off
	global_load_dwordx4 v[148:151], v[200:201], off offset:1024
	global_load_dwordx4 v[152:155], v[200:201], off offset:2048
	global_load_dwordx4 v[156:159], v[200:201], off offset:3072
	s_mov_b32 vcc_lo, 0x500000
	s_mov_b32 vcc_hi, 0
	v_lshl_add_u64 v[198:199], v[196:197], 0, vcc
	s_mov_b32 vcc_lo, 0x501000
	v_lshl_add_u64 v[200:201], v[196:197], 0, vcc
	global_load_dwordx4 v[160:163], v[198:199], off
	global_load_dwordx4 v[168:171], v[198:199], off offset:1024
	global_load_dwordx4 v[172:175], v[198:199], off offset:2048
	global_load_dwordx4 v[176:179], v[198:199], off offset:3072
	global_load_dwordx4 v[180:183], v[200:201], off
	global_load_dwordx4 v[184:187], v[200:201], off offset:1024
	global_load_dwordx4 v[188:191], v[200:201], off offset:2048
	global_load_dwordx4 v[192:195], v[200:201], off offset:3072
	s_waitcnt vmcnt(15)
	v_pk_add_f32 v[114:115], v[114:115], v[128:129]
	v_pk_add_f32 v[112:113], v[112:113], v[130:131]
	s_waitcnt vmcnt(14)
	v_pk_add_f32 v[108:109], v[108:109], v[132:133]
	v_pk_add_f32 v[106:107], v[106:107], v[134:135]
	s_waitcnt vmcnt(13)
	v_pk_add_f32 v[10:11], v[10:11], v[136:137]
	v_pk_add_f32 v[20:21], v[20:21], v[138:139]
	s_waitcnt vmcnt(12)
	v_pk_add_f32 v[16:17], v[16:17], v[140:141]
	v_pk_add_f32 v[18:19], v[18:19], v[142:143]
	s_waitcnt vmcnt(11)
	v_pk_add_f32 v[12:13], v[12:13], v[144:145]
	v_pk_add_f32 v[14:15], v[14:15], v[146:147]
	s_waitcnt vmcnt(10)
	v_pk_add_f32 v[22:23], v[22:23], v[148:149]
	v_pk_add_f32 v[8:9], v[8:9], v[150:151]
	s_waitcnt vmcnt(9)
	v_pk_add_f32 v[4:5], v[4:5], v[152:153]
	v_pk_add_f32 v[6:7], v[6:7], v[154:155]
	s_waitcnt vmcnt(8)
	v_pk_add_f32 v[0:1], v[0:1], v[156:157]
	v_pk_add_f32 v[2:3], v[2:3], v[158:159]
	s_waitcnt vmcnt(7)
	v_pk_add_f32 v[114:115], v[114:115], v[160:161]
	v_pk_add_f32 v[112:113], v[112:113], v[162:163]
	s_waitcnt vmcnt(6)
	v_pk_add_f32 v[108:109], v[108:109], v[168:169]
	v_pk_add_f32 v[106:107], v[106:107], v[170:171]
	s_waitcnt vmcnt(5)
	v_pk_add_f32 v[10:11], v[10:11], v[172:173]
	v_pk_add_f32 v[20:21], v[20:21], v[174:175]
	s_waitcnt vmcnt(4)
	v_pk_add_f32 v[16:17], v[16:17], v[176:177]
	v_pk_add_f32 v[18:19], v[18:19], v[178:179]
	s_waitcnt vmcnt(3)
	v_pk_add_f32 v[12:13], v[12:13], v[180:181]
	v_pk_add_f32 v[14:15], v[14:15], v[182:183]
	s_waitcnt vmcnt(2)
	v_pk_add_f32 v[22:23], v[22:23], v[184:185]
	v_pk_add_f32 v[8:9], v[8:9], v[186:187]
	s_waitcnt vmcnt(1)
	v_pk_add_f32 v[4:5], v[4:5], v[188:189]
	v_pk_add_f32 v[6:7], v[6:7], v[190:191]
	s_waitcnt vmcnt(0)
	v_pk_add_f32 v[0:1], v[0:1], v[192:193]
	v_pk_add_f32 v[2:3], v[2:3], v[194:195]
	s_mov_b32 vcc_lo, 0x600000
	s_mov_b32 vcc_hi, 0
	v_lshl_add_u64 v[198:199], v[196:197], 0, vcc
	s_mov_b32 vcc_lo, 0x601000
	v_lshl_add_u64 v[200:201], v[196:197], 0, vcc
	global_load_dwordx4 v[128:131], v[198:199], off
	global_load_dwordx4 v[132:135], v[198:199], off offset:1024
	global_load_dwordx4 v[136:139], v[198:199], off offset:2048
	global_load_dwordx4 v[140:143], v[198:199], off offset:3072
	global_load_dwordx4 v[144:147], v[200:201], off
	global_load_dwordx4 v[148:151], v[200:201], off offset:1024
	global_load_dwordx4 v[152:155], v[200:201], off offset:2048
	global_load_dwordx4 v[156:159], v[200:201], off offset:3072
	s_mov_b32 vcc_lo, 0x700000
	s_mov_b32 vcc_hi, 0
	v_lshl_add_u64 v[198:199], v[196:197], 0, vcc
	s_mov_b32 vcc_lo, 0x701000
	v_lshl_add_u64 v[200:201], v[196:197], 0, vcc
	global_load_dwordx4 v[160:163], v[198:199], off
	global_load_dwordx4 v[168:171], v[198:199], off offset:1024
	global_load_dwordx4 v[172:175], v[198:199], off offset:2048
	global_load_dwordx4 v[176:179], v[198:199], off offset:3072
	global_load_dwordx4 v[180:183], v[200:201], off
	global_load_dwordx4 v[184:187], v[200:201], off offset:1024
	global_load_dwordx4 v[188:191], v[200:201], off offset:2048
	global_load_dwordx4 v[192:195], v[200:201], off offset:3072
	s_waitcnt vmcnt(15)
	v_pk_add_f32 v[114:115], v[114:115], v[128:129]
	v_pk_add_f32 v[112:113], v[112:113], v[130:131]
	s_waitcnt vmcnt(14)
	v_pk_add_f32 v[108:109], v[108:109], v[132:133]
	v_pk_add_f32 v[106:107], v[106:107], v[134:135]
	s_waitcnt vmcnt(13)
	v_pk_add_f32 v[10:11], v[10:11], v[136:137]
	v_pk_add_f32 v[20:21], v[20:21], v[138:139]
	s_waitcnt vmcnt(12)
	v_pk_add_f32 v[16:17], v[16:17], v[140:141]
	v_pk_add_f32 v[18:19], v[18:19], v[142:143]
	s_waitcnt vmcnt(11)
	v_pk_add_f32 v[12:13], v[12:13], v[144:145]
	v_pk_add_f32 v[14:15], v[14:15], v[146:147]
	s_waitcnt vmcnt(10)
	v_pk_add_f32 v[22:23], v[22:23], v[148:149]
	v_pk_add_f32 v[8:9], v[8:9], v[150:151]
	s_waitcnt vmcnt(9)
	v_pk_add_f32 v[4:5], v[4:5], v[152:153]
	v_pk_add_f32 v[6:7], v[6:7], v[154:155]
	s_waitcnt vmcnt(8)
	v_pk_add_f32 v[0:1], v[0:1], v[156:157]
	v_pk_add_f32 v[2:3], v[2:3], v[158:159]
	s_waitcnt vmcnt(7)
	v_pk_add_f32 v[114:115], v[114:115], v[160:161]
	v_pk_add_f32 v[112:113], v[112:113], v[162:163]
	s_waitcnt vmcnt(6)
	v_pk_add_f32 v[108:109], v[108:109], v[168:169]
	v_pk_add_f32 v[106:107], v[106:107], v[170:171]
	s_waitcnt vmcnt(5)
	v_pk_add_f32 v[10:11], v[10:11], v[172:173]
	v_pk_add_f32 v[20:21], v[20:21], v[174:175]
	s_waitcnt vmcnt(4)
	v_pk_add_f32 v[16:17], v[16:17], v[176:177]
	v_pk_add_f32 v[18:19], v[18:19], v[178:179]
	s_waitcnt vmcnt(3)
	v_pk_add_f32 v[12:13], v[12:13], v[180:181]
	v_pk_add_f32 v[14:15], v[14:15], v[182:183]
	s_waitcnt vmcnt(2)
	v_pk_add_f32 v[22:23], v[22:23], v[184:185]
	v_pk_add_f32 v[8:9], v[8:9], v[186:187]
	s_waitcnt vmcnt(1)
	v_pk_add_f32 v[4:5], v[4:5], v[188:189]
	v_pk_add_f32 v[6:7], v[6:7], v[190:191]
	s_waitcnt vmcnt(0)
	v_pk_add_f32 v[0:1], v[0:1], v[192:193]
	v_pk_add_f32 v[2:3], v[2:3], v[194:195]
	v_mov_b32_e32 v101, v8
	v_mov_b32_e32 v100, v23
	v_mov_b32_e32 v8, v22
	v_mov_b32_e32 v102, v15
	v_mov_b32_e32 v104, v13
	v_mov_b32_e32 v111, v20
	v_mov_b32_e32 v110, v11
	v_mov_b32_e32 v20, v10
	v_mov_b32_e32 v26, v107
	v_mov_b32_e32 v24, v109
	v_mov_b32_e32 v27, v113
	v_mov_b32_e32 v107, v112
	v_mov_b32_e32 v25, v115
	v_mov_b32_e32 v109, v114
